# WG stagger config E: 4 groups in all four GEMM phases (phases 6/11: 0/3.5/7/10.5us)
# speedup vs baseline: 1.0084x; 1.0084x over previous
;   DI bf16_t* h() const { return (bf16_t*)(ws + OFF_H); }
; DI void phase_gemm_out(const Params& p, char* smem, const bf16_t* Wt, const float* R, float* O) {
;   u32x4 ra[4], rb[4]; bool pre = false;
;   for (int t = blockIdx.x; t < 64 * 8; t += gridDim.x) {
;     const int mt = t & 63, nt = t >> 6, tn = t + gridDim.x;
;     const bool has_next = tn < 64 * 8;
;     const GTile tl{p.h(), D, Wt, D, D, mt * 256, nt * 256}, nx{p.h(), D, Wt, D, D, (tn & 63) * 256, (tn >> 6) * 256};
;     WAVE_GEOM;
.Lstag_6_0:
	s_bitcmp1_b32 s84, 4
	s_cbranch_scc0 .Lstag_6_1
	s_sleep 127
	s_sleep 127
